# final RMS norm loop: gain vector loads hoisted out of the row loop, per-chunk vmcnt(0) drains removed
# speedup vs baseline: 1.0388x; 1.0070x over previous
; #define GAS __attribute__((address_space(1)))
; #define TID_SETUP() int tid_; asm volatile("v_mbcnt_lo_u32_b32 %0, -1, 0\n\tv_mbcnt_hi_u32_b32 %0, -1, %0" : "=&v"(tid_)); tid_ += wave0 * 64; const int tid = tid_, lane = tid & 63, wave = __builtin_amdgcn_readfirstlane(tid >> 6), gw = bx * 8 + wave; (void)lane; (void)gw
; __device__ __forceinline__ void rms_row_final(const bf16_t* xbrow, float* orow, const float* gain, const float* ssrow, int lane) {
;     GAS f32x4* xo = (GAS f32x4*)orow + 2 * lane; const GAS f32x4* gr = (const GAS f32x4*)gain + 2 * lane; const GAS u32x4* xr = (const GAS u32x4*)xbrow + lane;
;     u32x4 h[2];
; #pragma unroll
;     for (int j = 0; j < 2; ++j) h[j] = xr[64 * j];
;     const float s = lane < 16 ? *(const GAS float*)(ssrow + lane) : 0.f;
;     const float rstd = 1.0f / sqrtf(wave_sum(s) * (1.0f / D) + NORM_EPS);
; #pragma unroll
;     for (int j = 0; j < 2; ++j) {
;         const f32x4 a = (f32x4){__builtin_bit_cast(float, h[j].x << 16), __builtin_bit_cast(float, h[j].x & 0xffff0000u), __builtin_bit_cast(float, h[j].y << 16), __builtin_bit_cast(float, h[j].y & 0xffff0000u)};
;         const f32x4 b = (f32x4){__builtin_bit_cast(float, h[j].z << 16), __builtin_bit_cast(float, h[j].z & 0xffff0000u), __builtin_bit_cast(float, h[j].w << 16), __builtin_bit_cast(float, h[j].w & 0xffff0000u)};
;         xo[128 * j] = (a * rstd) * gr[128 * j]; xo[128 * j + 1] = (b * rstd) * gr[128 * j + 1]; }
; }
; __global__ void __launch_bounds__(512, 2) fwd_mega(Params P) {
;     ...
;     { TID_SETUP(); WS_SETUP();
;     for (int mrow = gw; mrow < M; mrow += NGW) rms_row_final(XB + (size_t)mrow * D, X + (size_t)mrow * D, P.in[3], SS + (size_t)mrow * 16, lane); }
.LBB0_1369:
	v_mbcnt_lo_u32_b32 v0, -1, 0
	v_mbcnt_hi_u32_b32 v0, -1, v0
	v_readlane_b32 s1, v254, 6
	v_add_u32_e32 v1, s93, v0
	s_nop 0
	v_readfirstlane_b32 s0, v1
	s_ashr_i32 s0, s0, 6
	s_add_i32 s4, s0, s1
	s_cmp_gt_i32 s4, 0xffff
	s_cbranch_scc1 .LBB0_1374
	v_and_b32_e32 v1, 64, v212
	v_add_u32_e32 v1, 64, v1
	v_xor_b32_e32 v4, 1, v212
	v_cmp_lt_i32_e32 vcc, v4, v1
	v_readlane_b32 s0, v254, 2
	v_readlane_b32 s1, v254, 3
	v_cndmask_b32_e32 v4, v212, v4, vcc
	v_lshlrev_b32_e32 v14, 2, v4
	v_xor_b32_e32 v4, 2, v212
	v_cmp_lt_i32_e32 vcc, v4, v1
	s_load_dwordx2 s[2:3], s[0:1], 0x88
	s_load_dwordx2 s[6:7], s[0:1], 0x18
	v_cndmask_b32_e32 v4, v212, v4, vcc
	v_lshlrev_b32_e32 v15, 2, v4
	v_xor_b32_e32 v4, 4, v212
	v_cmp_lt_i32_e32 vcc, v4, v1
	v_and_b32_e32 v0, 63, v0
	v_mov_b32_e32 v3, 0
	v_cndmask_b32_e32 v4, v212, v4, vcc
	v_lshlrev_b32_e32 v16, 2, v4
	v_xor_b32_e32 v4, 8, v212
	v_cmp_lt_i32_e32 vcc, v4, v1
	v_lshlrev_b32_e32 v2, 5, v0
	s_ashr_i32 s5, s4, 31
	v_cndmask_b32_e32 v4, v212, v4, vcc
	v_lshlrev_b32_e32 v17, 2, v4
	v_xor_b32_e32 v4, 16, v212
	v_cmp_lt_i32_e32 vcc, v4, v1
	s_waitcnt lgkmcnt(0)
	v_lshl_add_u64 v[8:9], s[6:7], 0, v[2:3]
	s_lshl_b64 s[6:7], s[4:5], 6
	v_cndmask_b32_e32 v4, v212, v4, vcc
	v_lshlrev_b32_e32 v18, 2, v4
	v_xor_b32_e32 v4, 32, v212
	v_cmp_lt_i32_e32 vcc, v4, v1
	s_add_u32 s6, s90, s6
	v_mov_b32_e32 v5, v3
	v_cndmask_b32_e32 v1, v212, v4, vcc
	v_lshlrev_b32_e32 v4, 2, v0
	s_addc_u32 s7, s91, s7
	v_lshl_add_u64 v[4:5], s[6:7], 0, v[4:5]
	s_mov_b64 s[6:7], 0x2d000000
	v_lshl_add_u64 v[10:11], v[4:5], 0, s[6:7]
	v_readlane_b32 s6, v254, 4
	v_readlane_b32 s7, v254, 5
	s_mov_b32 s14, s6
	s_ashr_i32 s15, s6, 31
	s_lshl_b64 s[6:7], s[14:15], 6
	s_lshl_b64 s[8:9], s[4:5], 11
	s_add_u32 s8, s90, s8
	s_addc_u32 s9, s91, s9
	s_add_u32 s8, s8, 0x25000000
	s_addc_u32 s9, s9, 0
	s_lshl_b64 s[10:11], s[14:15], 11
	s_lshl_b64 s[12:13], s[4:5], 12
	s_add_u32 s2, s2, s12
	s_addc_u32 s3, s3, s13
	v_lshl_add_u64 v[2:3], s[2:3], 0, v[2:3]
	s_mov_b64 s[2:3], 0x810
	v_cmp_gt_u32_e64 s[0:1], 16, v0
	v_lshlrev_b32_e32 v19, 2, v1
	v_lshl_add_u64 v[12:13], v[2:3], 0, s[2:3]
	s_mov_b32 s16, s14
	s_lshl_b64 s[12:13], s[14:15], 12
	v_lshlrev_b32_e32 v20, 4, v0
	v_mov_b32_e32 v21, 0x3727c5ac
	s_mov_b32 s5, 0xf800000
	v_mov_b32_e32 v22, 0x260
	global_load_dwordx4 v[36:39], v[8:9], off
	global_load_dwordx4 v[40:43], v[8:9], off offset:16
	global_load_dwordx4 v[44:47], v[8:9], off offset:2048
	global_load_dwordx4 v[48:51], v[8:9], off offset:2064
	s_branch .LBB0_1372
.LBB0_1371:
	s_or_b64 exec, exec, s[2:3]
	s_waitcnt vmcnt(0)
	ds_bpermute_b32 v28, v14, v23
	v_and_b32_e32 v29, 0xffff0000, v4
	s_add_i32 s4, s4, s16
	s_add_u32 s8, s8, s10
	s_addc_u32 s9, s9, s11
	s_waitcnt lgkmcnt(0)
	v_add_f32_e32 v23, v23, v28
	ds_bpermute_b32 v28, v15, v23
	v_lshl_add_u64 v[10:11], v[10:11], 0, s[6:7]
	s_cmp_gt_i32 s4, 0xffff
	s_waitcnt lgkmcnt(0)
	v_add_f32_e32 v23, v23, v28
	ds_bpermute_b32 v28, v16, v23
	s_waitcnt lgkmcnt(0)
	v_add_f32_e32 v23, v23, v28
	ds_bpermute_b32 v28, v17, v23
	s_waitcnt lgkmcnt(0)
	v_add_f32_e32 v23, v23, v28
	ds_bpermute_b32 v28, v18, v23
	s_waitcnt lgkmcnt(0)
	v_add_f32_e32 v23, v23, v28
	ds_bpermute_b32 v28, v19, v23
	s_waitcnt lgkmcnt(0)
	v_add_f32_e32 v23, v23, v28
	v_fmamk_f32 v23, v23, 0x3a800000, v21
	v_mul_f32_e32 v28, 0x4f800000, v23
	v_cmp_gt_f32_e32 vcc, s5, v23
	s_nop 1
	v_cndmask_b32_e32 v23, v23, v28, vcc
	v_sqrt_f32_e32 v30, v23
	v_lshlrev_b32_e32 v28, 16, v4
	v_lshlrev_b32_e32 v4, 16, v5
	v_and_b32_e32 v5, 0xffff0000, v5
	v_add_u32_e32 v31, -1, v30
	v_add_u32_e32 v32, 1, v30
	v_fma_f32 v33, -v31, v30, v23
	v_fma_f32 v34, -v32, v30, v23
	v_cmp_ge_f32_e64 s[2:3], 0, v33
	s_nop 1
	v_cndmask_b32_e64 v30, v30, v31, s[2:3]
	v_cmp_lt_f32_e64 s[2:3], 0, v34
	s_nop 1
	v_cndmask_b32_e64 v30, v30, v32, s[2:3]
	v_mul_f32_e32 v31, 0x37800000, v30
	v_cndmask_b32_e32 v30, v30, v31, vcc
	v_cmp_class_f32_e32 vcc, v23, v22
	s_nop 1
	v_cndmask_b32_e32 v23, v30, v23, vcc
	v_div_scale_f32 v30, s[2:3], v23, v23, 1.0
	v_rcp_f32_e32 v31, v30
	v_div_scale_f32 v32, vcc, 1.0, v23, 1.0
	v_fma_f32 v33, -v30, v31, 1.0
	v_fmac_f32_e32 v31, v33, v31
	v_mul_f32_e32 v33, v32, v31
	v_fma_f32 v34, -v30, v33, v32
	v_fmac_f32_e32 v33, v34, v31
	v_fma_f32 v30, -v30, v33, v32
	v_div_fmas_f32 v30, v30, v31, v33
	v_div_fixup_f32 v30, v30, v23, 1.0
	v_pk_mul_f32 v[28:29], v[30:31], v[28:29] op_sel_hi:[0,1]
	v_pk_mul_f32 v[4:5], v[30:31], v[4:5] op_sel_hi:[0,1]
	v_pk_mul_f32 v[26:27], v[38:39], v[4:5]
	v_pk_mul_f32 v[24:25], v[36:37], v[28:29]
	global_store_dwordx4 v[12:13], v[24:27], off offset:-2064
	v_lshlrev_b32_e32 v4, 16, v6
	v_and_b32_e32 v5, 0xffff0000, v6
	v_lshlrev_b32_e32 v6, 16, v7
	v_and_b32_e32 v7, 0xffff0000, v7
	v_pk_mul_f32 v[6:7], v[30:31], v[6:7] op_sel_hi:[0,1]
	v_pk_mul_f32 v[4:5], v[30:31], v[4:5] op_sel_hi:[0,1]
	v_pk_mul_f32 v[4:5], v[40:41], v[4:5]
	v_pk_mul_f32 v[6:7], v[42:43], v[6:7]
	global_store_dwordx4 v[12:13], v[4:7], off offset:-2048
	v_lshlrev_b32_e32 v24, 16, v0
	v_and_b32_e32 v25, 0xffff0000, v0
	v_lshlrev_b32_e32 v0, 16, v1
	v_and_b32_e32 v1, 0xffff0000, v1
	v_pk_mul_f32 v[0:1], v[30:31], v[0:1] op_sel_hi:[0,1]
	v_pk_mul_f32 v[24:25], v[30:31], v[24:25] op_sel_hi:[0,1]
	v_pk_mul_f32 v[4:5], v[44:45], v[24:25]
	v_pk_mul_f32 v[6:7], v[46:47], v[0:1]
	global_store_dwordx4 v[12:13], v[4:7], off offset:-16
	v_lshlrev_b32_e32 v0, 16, v2
	v_and_b32_e32 v1, 0xffff0000, v2
	v_lshlrev_b32_e32 v2, 16, v3
	v_and_b32_e32 v3, 0xffff0000, v3
	v_pk_mul_f32 v[2:3], v[30:31], v[2:3] op_sel_hi:[0,1]
	v_pk_mul_f32 v[0:1], v[30:31], v[0:1] op_sel_hi:[0,1]
	v_pk_mul_f32 v[0:1], v[48:49], v[0:1]
	v_pk_mul_f32 v[2:3], v[50:51], v[2:3]
	global_store_dwordx4 v[12:13], v[0:3], off
	v_lshl_add_u64 v[12:13], v[12:13], 0, s[12:13]
	s_cbranch_scc1 .LBB0_1374
